# phase 14 LN2 write pass: ln_w/ln_b loads of the next column step hoisted above the current step's store into spare registers, counted vmcnt(1) wait (on top of the same change in phase 11)
# speedup vs baseline: 1.0071x; 1.0071x over previous
.LBB0_1019:
	global_load_dwordx2 v[72:73], v[52:53], off
	global_load_dwordx2 v[74:75], v[52:53], off offset:512
	global_load_dwordx2 v[76:77], v[52:53], off offset:1024
	global_load_dwordx2 v[78:79], v[52:53], off offset:1536
	v_add_co_u32_e32 v80, vcc, 0x1000, v52
	global_load_dwordx2 v[82:83], v[52:53], off offset:2048
	global_load_dwordx4 v[20:23], v[54:55], off offset:-4096
	global_load_dwordx4 v[16:19], v[54:55], off offset:-3072
	global_load_dwordx4 v[12:15], v[54:55], off offset:-2048
	global_load_dwordx4 v[8:11], v[54:55], off offset:-1024
	global_load_dwordx2 v[84:85], v[52:53], off offset:2560
	global_load_dwordx4 v[28:31], v[54:55], off
	global_load_dwordx4 v[24:27], v[54:55], off offset:1024
	global_load_dwordx2 v[86:87], v[52:53], off offset:3072
	global_load_dwordx4 v[64:67], v[54:55], off offset:2048
	global_load_dwordx4 v[68:71], v[54:55], off offset:3072
	global_load_dwordx2 v[88:89], v[52:53], off offset:3584
	global_load_dwordx4 v[0:3], v[32:33], off
	global_load_dwordx4 v[4:7], v[34:35], off
	v_addc_co_u32_e32 v81, vcc, 0, v53, vcc
	global_load_dwordx2 v[90:91], v[80:81], off
	global_load_dwordx2 v[92:93], v[80:81], off offset:512
	global_load_dwordx2 v[94:95], v[80:81], off offset:1024
	global_load_dwordx2 v[96:97], v[80:81], off offset:1536
	global_load_dwordx2 v[98:99], v[80:81], off offset:2048
	global_load_dwordx2 v[100:101], v[80:81], off offset:2560
	global_load_dwordx2 v[102:103], v[80:81], off offset:3072
	global_load_dwordx2 v[104:105], v[80:81], off offset:3584
	v_add_u32_e32 v56, s6, v56
	v_lshl_add_u64 v[52:53], v[52:53], 0, s[0:1]
	s_waitcnt vmcnt(21)
	v_lshlrev_b32_e32 v112, 16, v82
	v_and_b32_e32 v113, 0xffff0000, v82
	v_lshlrev_b32_e32 v82, 16, v83
	v_and_b32_e32 v83, 0xffff0000, v83
	s_waitcnt vmcnt(16)
	v_lshlrev_b32_e32 v114, 16, v84
	v_and_b32_e32 v115, 0xffff0000, v84
	v_lshlrev_b32_e32 v80, 16, v72
	v_and_b32_e32 v81, 0xffff0000, v72
	s_waitcnt vmcnt(7)
	v_lshlrev_b32_e32 v120, 16, v90
	v_and_b32_e32 v121, 0xffff0000, v90
	v_lshlrev_b32_e32 v72, 16, v73
	v_and_b32_e32 v73, 0xffff0000, v73
	v_lshlrev_b32_e32 v90, 16, v91
	v_and_b32_e32 v91, 0xffff0000, v91
	v_pk_add_f32 v[80:81], v[80:81], v[120:121]
	v_pk_add_f32 v[72:73], v[72:73], v[90:91]
	v_pk_add_f32 v[20:21], v[20:21], v[80:81]
	v_pk_add_f32 v[22:23], v[22:23], v[72:73]
	v_add_f32_e32 v72, 0, v20
	v_lshlrev_b32_e32 v106, 16, v74
	v_and_b32_e32 v107, 0xffff0000, v74
	s_waitcnt vmcnt(6)
	v_lshlrev_b32_e32 v122, 16, v92
	v_and_b32_e32 v123, 0xffff0000, v92
	v_add_f32_e32 v72, v21, v72
	v_pk_add_f32 v[90:91], v[106:107], v[122:123]
	v_add_f32_e32 v72, v22, v72
	v_lshlrev_b32_e32 v74, 16, v75
	v_and_b32_e32 v75, 0xffff0000, v75
	v_lshlrev_b32_e32 v92, 16, v93
	v_and_b32_e32 v93, 0xffff0000, v93
	v_pk_add_f32 v[16:17], v[16:17], v[90:91]
	v_add_f32_e32 v72, v23, v72
	v_pk_add_f32 v[74:75], v[74:75], v[92:93]
	v_add_f32_e32 v72, v72, v16
	v_lshlrev_b32_e32 v108, 16, v76
	v_and_b32_e32 v109, 0xffff0000, v76
	s_waitcnt vmcnt(5)
	v_lshlrev_b32_e32 v124, 16, v94
	v_and_b32_e32 v125, 0xffff0000, v94
	v_pk_add_f32 v[18:19], v[18:19], v[74:75]
	v_add_f32_e32 v72, v17, v72
	v_pk_add_f32 v[92:93], v[108:109], v[124:125]
	v_add_f32_e32 v72, v18, v72
	v_lshlrev_b32_e32 v76, 16, v77
	v_and_b32_e32 v77, 0xffff0000, v77
	v_lshlrev_b32_e32 v94, 16, v95
	v_and_b32_e32 v95, 0xffff0000, v95
	v_pk_add_f32 v[12:13], v[12:13], v[92:93]
	v_add_f32_e32 v72, v19, v72
	v_pk_add_f32 v[76:77], v[76:77], v[94:95]
	v_add_f32_e32 v72, v72, v12
	v_lshlrev_b32_e32 v110, 16, v78
	v_and_b32_e32 v111, 0xffff0000, v78
	s_waitcnt vmcnt(4)
	v_lshlrev_b32_e32 v126, 16, v96
	v_and_b32_e32 v127, 0xffff0000, v96
	v_pk_add_f32 v[14:15], v[14:15], v[76:77]
	v_add_f32_e32 v72, v13, v72
	v_pk_add_f32 v[94:95], v[110:111], v[126:127]
	v_add_f32_e32 v72, v14, v72
	v_lshlrev_b32_e32 v78, 16, v79
	v_and_b32_e32 v79, 0xffff0000, v79
	v_lshlrev_b32_e32 v96, 16, v97
	v_and_b32_e32 v97, 0xffff0000, v97
	v_pk_add_f32 v[8:9], v[8:9], v[94:95]
	v_add_f32_e32 v72, v15, v72
	v_pk_add_f32 v[78:79], v[78:79], v[96:97]
	v_add_f32_e32 v72, v72, v8
	s_waitcnt vmcnt(3)
	v_lshlrev_b32_e32 v128, 16, v98
	v_and_b32_e32 v129, 0xffff0000, v98
	v_pk_add_f32 v[10:11], v[10:11], v[78:79]
	v_add_f32_e32 v72, v9, v72
	v_pk_add_f32 v[96:97], v[112:113], v[128:129]
	v_add_f32_e32 v72, v10, v72
	v_lshlrev_b32_e32 v98, 16, v99
	v_and_b32_e32 v99, 0xffff0000, v99
	v_pk_add_f32 v[28:29], v[28:29], v[96:97]
	v_add_f32_e32 v72, v11, v72
	v_pk_add_f32 v[82:83], v[82:83], v[98:99]
	v_add_f32_e32 v72, v72, v28
	s_waitcnt vmcnt(2)
	v_lshlrev_b32_e32 v130, 16, v100
	v_and_b32_e32 v131, 0xffff0000, v100
	v_pk_add_f32 v[30:31], v[30:31], v[82:83]
	v_add_f32_e32 v72, v29, v72
	v_pk_add_f32 v[98:99], v[114:115], v[130:131]
	v_add_f32_e32 v72, v30, v72
	v_lshlrev_b32_e32 v84, 16, v85
	v_and_b32_e32 v85, 0xffff0000, v85
	v_lshlrev_b32_e32 v100, 16, v101
	v_and_b32_e32 v101, 0xffff0000, v101
	v_pk_add_f32 v[24:25], v[24:25], v[98:99]
	v_add_f32_e32 v72, v31, v72
	v_pk_add_f32 v[84:85], v[84:85], v[100:101]
	v_add_f32_e32 v72, v72, v24
	v_lshlrev_b32_e32 v116, 16, v86
	v_and_b32_e32 v117, 0xffff0000, v86
	s_waitcnt vmcnt(1)
	v_lshlrev_b32_e32 v132, 16, v102
	v_and_b32_e32 v133, 0xffff0000, v102
	v_pk_add_f32 v[26:27], v[26:27], v[84:85]
	v_add_f32_e32 v72, v25, v72
	v_pk_add_f32 v[100:101], v[116:117], v[132:133]
	v_add_f32_e32 v72, v26, v72
	v_lshlrev_b32_e32 v86, 16, v87
	v_and_b32_e32 v87, 0xffff0000, v87
	v_lshlrev_b32_e32 v102, 16, v103
	v_and_b32_e32 v103, 0xffff0000, v103
	v_pk_add_f32 v[64:65], v[64:65], v[100:101]
	v_add_f32_e32 v72, v27, v72
	v_pk_add_f32 v[86:87], v[86:87], v[102:103]
	v_add_f32_e32 v72, v72, v64
	v_lshlrev_b32_e32 v118, 16, v88
	v_and_b32_e32 v119, 0xffff0000, v88
	s_waitcnt vmcnt(0)
	v_lshlrev_b32_e32 v134, 16, v104
	v_and_b32_e32 v135, 0xffff0000, v104
	v_pk_add_f32 v[66:67], v[66:67], v[86:87]
	v_add_f32_e32 v72, v65, v72
	v_pk_add_f32 v[118:119], v[118:119], v[134:135]
	v_add_f32_e32 v72, v66, v72
	v_lshlrev_b32_e32 v88, 16, v89
	v_and_b32_e32 v89, 0xffff0000, v89
	v_lshlrev_b32_e32 v104, 16, v105
	v_and_b32_e32 v105, 0xffff0000, v105
	v_pk_add_f32 v[68:69], v[68:69], v[118:119]
	v_add_f32_e32 v72, v67, v72
	v_pk_add_f32 v[88:89], v[88:89], v[104:105]
	v_add_f32_e32 v72, v72, v68
	v_pk_add_f32 v[70:71], v[70:71], v[88:89]
	v_add_f32_e32 v72, v69, v72
	v_add_f32_e32 v72, v70, v72
	v_add_f32_e32 v72, v71, v72
	ds_bpermute_b32 v73, v57, v72
	s_waitcnt lgkmcnt(0)
	v_add_f32_e32 v72, v72, v73
	ds_bpermute_b32 v73, v58, v72
	s_waitcnt lgkmcnt(0)
	v_add_f32_e32 v72, v72, v73
	ds_bpermute_b32 v73, v59, v72
	s_waitcnt lgkmcnt(0)
	v_add_f32_e32 v72, v72, v73
	ds_bpermute_b32 v73, v60, v72
	s_waitcnt lgkmcnt(0)
	v_add_f32_e32 v72, v72, v73
	ds_bpermute_b32 v73, v61, v72
	s_waitcnt lgkmcnt(0)
	v_add_f32_e32 v72, v72, v73
	ds_bpermute_b32 v73, v62, v72
	s_waitcnt lgkmcnt(0)
	v_add_f32_e32 v72, v72, v73
	v_mul_f32_e32 v72, 0x3a000000, v72
	v_pk_add_f32 v[20:21], v[20:21], v[72:73] op_sel_hi:[1,0] neg_lo:[0,1] neg_hi:[0,1]
	v_pk_add_f32 v[22:23], v[22:23], v[72:73] op_sel_hi:[1,0] neg_lo:[0,1] neg_hi:[0,1]
	v_pk_add_f32 v[16:17], v[16:17], v[72:73] op_sel_hi:[1,0] neg_lo:[0,1] neg_hi:[0,1]
	v_pk_add_f32 v[18:19], v[18:19], v[72:73] op_sel_hi:[1,0] neg_lo:[0,1] neg_hi:[0,1]
	v_pk_add_f32 v[12:13], v[12:13], v[72:73] op_sel_hi:[1,0] neg_lo:[0,1] neg_hi:[0,1]
	v_pk_add_f32 v[14:15], v[14:15], v[72:73] op_sel_hi:[1,0] neg_lo:[0,1] neg_hi:[0,1]
	v_pk_add_f32 v[8:9], v[8:9], v[72:73] op_sel_hi:[1,0] neg_lo:[0,1] neg_hi:[0,1]
	v_pk_add_f32 v[10:11], v[10:11], v[72:73] op_sel_hi:[1,0] neg_lo:[0,1] neg_hi:[0,1]
	v_pk_add_f32 v[28:29], v[28:29], v[72:73] op_sel_hi:[1,0] neg_lo:[0,1] neg_hi:[0,1]
	v_pk_add_f32 v[30:31], v[30:31], v[72:73] op_sel_hi:[1,0] neg_lo:[0,1] neg_hi:[0,1]
	v_pk_add_f32 v[24:25], v[24:25], v[72:73] op_sel_hi:[1,0] neg_lo:[0,1] neg_hi:[0,1]
	v_pk_add_f32 v[26:27], v[26:27], v[72:73] op_sel_hi:[1,0] neg_lo:[0,1] neg_hi:[0,1]
	v_pk_add_f32 v[64:65], v[64:65], v[72:73] op_sel_hi:[1,0] neg_lo:[0,1] neg_hi:[0,1]
	v_pk_add_f32 v[66:67], v[66:67], v[72:73] op_sel_hi:[1,0] neg_lo:[0,1] neg_hi:[0,1]
	v_pk_add_f32 v[68:69], v[68:69], v[72:73] op_sel_hi:[1,0] neg_lo:[0,1] neg_hi:[0,1]
	v_pk_add_f32 v[70:71], v[70:71], v[72:73] op_sel_hi:[1,0] neg_lo:[0,1] neg_hi:[0,1]
	v_pk_mul_f32 v[72:73], v[20:21], v[20:21]
	v_pk_mul_f32 v[74:75], v[22:23], v[22:23]
	v_add_f32_e32 v72, v72, v73
	v_add_f32_e32 v72, v74, v72
	v_pk_mul_f32 v[76:77], v[16:17], v[16:17]
	v_add_f32_e32 v72, v75, v72
	v_add_f32_e32 v72, v76, v72
	v_pk_mul_f32 v[78:79], v[18:19], v[18:19]
	v_add_f32_e32 v72, v77, v72
	v_add_f32_e32 v72, v78, v72
	v_pk_mul_f32 v[80:81], v[12:13], v[12:13]
	v_add_f32_e32 v72, v79, v72
	v_add_f32_e32 v72, v80, v72
	v_pk_mul_f32 v[82:83], v[14:15], v[14:15]
	v_add_f32_e32 v72, v81, v72
	v_add_f32_e32 v72, v82, v72
	v_pk_mul_f32 v[84:85], v[8:9], v[8:9]
	v_add_f32_e32 v72, v83, v72
	v_add_f32_e32 v72, v84, v72
	v_pk_mul_f32 v[86:87], v[10:11], v[10:11]
	v_add_f32_e32 v72, v85, v72
	v_add_f32_e32 v72, v86, v72
	v_pk_mul_f32 v[88:89], v[28:29], v[28:29]
	v_add_f32_e32 v72, v87, v72
	v_add_f32_e32 v72, v88, v72
	v_pk_mul_f32 v[90:91], v[30:31], v[30:31]
	v_add_f32_e32 v72, v89, v72
	v_add_f32_e32 v72, v90, v72
	v_pk_mul_f32 v[92:93], v[24:25], v[24:25]
	v_add_f32_e32 v72, v91, v72
	v_add_f32_e32 v72, v92, v72
	v_pk_mul_f32 v[94:95], v[26:27], v[26:27]
	v_add_f32_e32 v72, v93, v72
	v_add_f32_e32 v72, v94, v72
	v_pk_mul_f32 v[96:97], v[64:65], v[64:65]
	v_add_f32_e32 v72, v95, v72
	v_add_f32_e32 v72, v96, v72
	v_pk_mul_f32 v[98:99], v[66:67], v[66:67]
	v_add_f32_e32 v72, v97, v72
	v_add_f32_e32 v72, v98, v72
	v_pk_mul_f32 v[100:101], v[68:69], v[68:69]
	v_add_f32_e32 v72, v99, v72
	v_add_f32_e32 v72, v100, v72
	v_pk_mul_f32 v[102:103], v[70:71], v[70:71]
	v_add_f32_e32 v72, v101, v72
	v_add_f32_e32 v72, v102, v72
	v_add_f32_e32 v72, v103, v72
	ds_bpermute_b32 v73, v57, v72
	s_waitcnt lgkmcnt(0)
	v_add_f32_e32 v72, v72, v73
	ds_bpermute_b32 v73, v58, v72
	s_waitcnt lgkmcnt(0)
	v_add_f32_e32 v72, v72, v73
	ds_bpermute_b32 v73, v59, v72
	s_waitcnt lgkmcnt(0)
	v_add_f32_e32 v72, v72, v73
	ds_bpermute_b32 v73, v60, v72
	s_waitcnt lgkmcnt(0)
	v_add_f32_e32 v72, v72, v73
	ds_bpermute_b32 v73, v61, v72
	s_waitcnt lgkmcnt(0)
	v_add_f32_e32 v72, v72, v73
	ds_bpermute_b32 v73, v62, v72
	s_waitcnt lgkmcnt(0)
	v_add_f32_e32 v72, v72, v73
	v_fmamk_f32 v72, v72, 0x3a000000, v63
	v_mul_f32_e32 v73, 0x4b800000, v72
	v_cmp_gt_f32_e32 vcc, s7, v72
	s_nop 1
	v_cndmask_b32_e32 v72, v72, v73, vcc
	v_rsq_f32_e32 v72, v72
	s_nop 0
	v_mul_f32_e32 v73, 0x45800000, v72
	v_cndmask_b32_e32 v72, v72, v73, vcc
	v_pk_mul_f32 v[20:21], v[20:21], v[72:73] op_sel_hi:[1,0]
	v_pk_mul_f32 v[22:23], v[22:23], v[72:73] op_sel_hi:[1,0]
	v_pk_fma_f32 v[0:1], v[0:1], v[20:21], v[4:5]
	v_pk_fma_f32 v[2:3], v[2:3], v[22:23], v[6:7]
	global_load_dwordx4 v[244:247], v[32:33], off offset:1024
	global_load_dwordx4 v[248:251], v[34:35], off offset:1024
	global_store_dwordx4 v[54:55], v[0:3], off offset:-4096
	s_nop 0
	v_pk_mul_f32 v[18:19], v[18:19], v[72:73] op_sel_hi:[1,0]
	v_pk_mul_f32 v[16:17], v[16:17], v[72:73] op_sel_hi:[1,0]
	v_pk_mul_f32 v[14:15], v[14:15], v[72:73] op_sel_hi:[1,0]
	v_pk_mul_f32 v[12:13], v[12:13], v[72:73] op_sel_hi:[1,0]
	v_pk_mul_f32 v[10:11], v[10:11], v[72:73] op_sel_hi:[1,0]
	v_pk_mul_f32 v[8:9], v[8:9], v[72:73] op_sel_hi:[1,0]
	v_cmp_lt_u32_e32 vcc, s8, v56
	s_or_b64 s[4:5], vcc, s[4:5]
	s_waitcnt vmcnt(1)
	s_nop 1
	v_pk_fma_f32 v[0:1], v[244:245], v[16:17], v[248:249]
	v_pk_fma_f32 v[2:3], v[246:247], v[18:19], v[250:251]
	global_load_dwordx4 v[244:247], v[32:33], off offset:2048
	global_load_dwordx4 v[248:251], v[34:35], off offset:2048
	global_store_dwordx4 v[54:55], v[0:3], off offset:-3072
	s_nop 0
	s_waitcnt vmcnt(1)
	s_nop 1
	v_pk_fma_f32 v[0:1], v[244:245], v[12:13], v[248:249]
	v_pk_fma_f32 v[2:3], v[246:247], v[14:15], v[250:251]
	global_load_dwordx4 v[244:247], v[32:33], off offset:3072
	global_load_dwordx4 v[248:251], v[34:35], off offset:3072
	global_store_dwordx4 v[54:55], v[0:3], off offset:-2048
	s_nop 0
	s_waitcnt vmcnt(1)
	s_nop 1
	v_pk_fma_f32 v[0:1], v[244:245], v[8:9], v[248:249]
	v_pk_fma_f32 v[2:3], v[246:247], v[10:11], v[250:251]
	global_load_dwordx4 v[244:247], v[36:37], off
	global_load_dwordx4 v[248:251], v[38:39], off
	global_store_dwordx4 v[54:55], v[0:3], off offset:-1024
	s_nop 0
	v_pk_mul_f32 v[8:9], v[30:31], v[72:73] op_sel_hi:[1,0]
	v_pk_mul_f32 v[10:11], v[28:29], v[72:73] op_sel_hi:[1,0]
	s_waitcnt vmcnt(1)
	s_nop 1
	v_pk_fma_f32 v[2:3], v[246:247], v[8:9], v[250:251]
	v_pk_fma_f32 v[0:1], v[244:245], v[10:11], v[248:249]
	global_load_dwordx4 v[244:247], v[40:41], off
	global_load_dwordx4 v[248:251], v[42:43], off
	global_store_dwordx4 v[54:55], v[0:3], off
	s_nop 0
	v_pk_mul_f32 v[8:9], v[26:27], v[72:73] op_sel_hi:[1,0]
	v_pk_mul_f32 v[10:11], v[24:25], v[72:73] op_sel_hi:[1,0]
	s_waitcnt vmcnt(1)
	s_nop 1
	v_pk_fma_f32 v[2:3], v[246:247], v[8:9], v[250:251]
	v_pk_fma_f32 v[0:1], v[244:245], v[10:11], v[248:249]
	global_load_dwordx4 v[244:247], v[44:45], off
	global_load_dwordx4 v[248:251], v[46:47], off
	global_store_dwordx4 v[54:55], v[0:3], off offset:1024
	s_nop 0
	v_pk_mul_f32 v[8:9], v[66:67], v[72:73] op_sel_hi:[1,0]
	v_pk_mul_f32 v[10:11], v[64:65], v[72:73] op_sel_hi:[1,0]
	s_waitcnt vmcnt(1)
	s_nop 1
	v_pk_fma_f32 v[2:3], v[246:247], v[8:9], v[250:251]
	v_pk_fma_f32 v[0:1], v[244:245], v[10:11], v[248:249]
	global_load_dwordx4 v[244:247], v[48:49], off
	global_load_dwordx4 v[248:251], v[50:51], off
	global_store_dwordx4 v[54:55], v[0:3], off offset:2048
	s_nop 0
	v_pk_mul_f32 v[8:9], v[70:71], v[72:73] op_sel_hi:[1,0]
	v_pk_mul_f32 v[10:11], v[68:69], v[72:73] op_sel_hi:[1,0]
	s_waitcnt vmcnt(1)
	s_nop 1
	v_pk_fma_f32 v[2:3], v[246:247], v[8:9], v[250:251]
	v_pk_fma_f32 v[0:1], v[244:245], v[10:11], v[248:249]
	global_store_dwordx4 v[54:55], v[0:3], off offset:3072
	v_lshl_add_u64 v[54:55], v[54:55], 0, s[2:3]
	s_andn2_b64 exec, exec, s[4:5]
	s_cbranch_execnz .LBB0_1019
